# GEMM tile-pipeline prologue de-serialised at 8 sites: all 14 LDS-DMA stage loads issued before the first wait (vmcnt(8)+barrier sunk below the second stage group)
# baseline (speedup 1.0000x reference)
.LBB0_200:
	s_add_u32 s49, s33, 0x1a000000
	s_addc_u32 s50, s34, 0
	s_add_u32 s51, s33, 0x26000000
	s_addc_u32 s52, s34, 0
	s_lshl_b32 s4, s4, 5
	s_add_i32 s54, s37, 0x18000
	s_mov_b64 s[14:15], 0x80
	s_and_b32 s53, s4, 0x60
	v_lshl_add_u64 v[8:9], v[8:9], 0, s[14:15]
	s_mov_b32 m0, s54
	s_add_i32 s55, s37, 0x1a000
	s_lshl_b32 s8, s3, 13
	s_lshl_b32 s9, s53, 7
	global_load_lds_dwordx4 v[8:9], off
	v_lshl_add_u64 v[6:7], v[6:7], 0, s[14:15]
	s_mov_b32 m0, s55
	s_add_i32 s58, s37, 0x8000
	s_add_i32 s59, s37, 0xa000
	global_load_lds_dwordx4 v[6:7], off
	v_lshl_add_u64 v[2:3], v[2:3], 0, s[14:15]
	s_mov_b32 m0, s58
	s_add_u32 s4, s28, 0x80080
	global_load_lds_dwordx4 v[2:3], off
	v_lshl_add_u64 v[2:3], v[4:5], 0, s[14:15]
	s_mov_b32 m0, s59
	s_addc_u32 s5, s29, 0
	s_add_i32 s60, s37, 0x1c000
	global_load_lds_dwordx4 v[2:3], off
	v_lshl_add_u64 v[2:3], s[4:5], 0, v[198:199]
	s_mov_b32 m0, s60
	s_add_i32 s61, s37, 0x1e000
	global_load_lds_dwordx4 v[2:3], off
	v_lshl_add_u64 v[2:3], s[4:5], 0, v[202:203]
	s_mov_b32 m0, s61
	v_and_b32_e32 v216, 15, v1
	global_load_lds_dwordx4 v[2:3], off
	v_bfe_u32 v217, v1, 4, 2
	v_lshlrev_b32_e32 v2, 6, v216
	v_lshlrev_b32_e32 v1, 2, v1
	v_lshl_or_b32 v2, v217, 4, v2
	v_and_b32_e32 v1, 32, v1
	v_bitop3_b32 v3, v2, s8, v1 bitop3:0xde
	v_bitop3_b32 v1, v2, s9, v1 bitop3:0xde
	v_lshlrev_b32_e32 v2, 15, v10
	v_and_b32_e32 v2, 0xffff0000, v2
	v_lshl_add_u32 v2, v11, 12, v2
	v_and_b32_e32 v4, 1, v10
	v_lshl_or_b32 v2, v4, 6, v2
	v_lshl_add_u32 v204, v12, 1, v2
	v_lshlrev_b32_e32 v2, 15, v13
	v_and_b32_e32 v2, 0xffff0000, v2
	s_waitcnt vmcnt(8)
	s_barrier
	s_waitcnt vmcnt(6)
	s_cmpk_lt_u32 s1, 0x100
	v_lshl_add_u32 v2, v14, 12, v2
	v_and_b32_e32 v4, 1, v13
	s_cselect_b64 s[16:17], -1, 0
	s_lshl_b32 s1, s3, 17
	v_lshl_or_b32 v2, v4, 6, v2
	v_add_u32_e32 v218, 0, v1
	s_movk_i32 s62, 0x60
	s_lshl_b32 s63, s3, 15
	s_or_b32 s64, s53, s1
	v_mov_b32_e32 v205, v0
	v_lshl_add_u32 v206, v15, 1, v2
	v_mov_b32_e32 v207, v0
	v_add_u32_e32 v219, 0x10000, v218
	v_add_u32_e32 v220, 0x14000, v218
	v_add_u32_e32 v221, 0, v3
	s_movk_i32 s65, 0x180
	s_movk_i32 s66, 0x80
	s_mov_b32 s67, 0x7fffff7f
	s_mov_b32 s68, 0
	s_mov_b64 s[22:23], s[28:29]
	s_mov_b64 s[20:21], s[6:7]
	s_barrier
	s_branch .LBB0_203

.LBB0_388:
	s_add_u32 s44, s36, 0xe000000
	s_addc_u32 s45, s37, 0
	s_lshl_b32 s5, s11, 5
	s_mov_b64 s[22:23], 0x80
	s_and_b32 s46, s5, 0x60
	s_add_i32 m0, s0, 0x18000
	v_lshl_add_u64 v[6:7], v[6:7], 0, s[22:23]
	s_lshl_b32 s24, s10, 13
	s_lshl_b32 s11, s46, 7
	global_load_lds_dwordx4 v[6:7], off
	v_lshl_add_u64 v[4:5], v[4:5], 0, s[22:23]
	s_add_i32 m0, s0, 0x1a000
	s_add_i32 s47, s0, 0x8000
	s_add_i32 s48, s0, 0xa000
	global_load_lds_dwordx4 v[4:5], off
	v_lshl_add_u64 v[0:1], v[0:1], 0, s[22:23]
	s_mov_b32 m0, s47
	s_add_u32 s12, s20, 0x20080
	global_load_lds_dwordx4 v[0:1], off
	v_lshl_add_u64 v[0:1], v[2:3], 0, s[22:23]
	s_mov_b32 m0, s48
	s_addc_u32 s13, s21, 0
	global_load_lds_dwordx4 v[0:1], off
	s_add_i32 m0, s0, 0x1c000
	v_lshl_add_u64 v[0:1], s[12:13], 0, v[140:141]
	global_load_lds_dwordx4 v[0:1], off
	v_lshl_add_u64 v[0:1], s[12:13], 0, v[136:137]
	s_add_i32 m0, s0, 0x1e000
	v_and_b32_e32 v161, 15, v8
	global_load_lds_dwordx4 v[0:1], off
	v_bfe_u32 v160, v8, 4, 2
	v_lshlrev_b32_e32 v0, 6, v161
	v_lshlrev_b32_e32 v1, 2, v8
	v_lshl_or_b32 v0, v160, 4, v0
	v_and_b32_e32 v1, 32, v1
	s_waitcnt vmcnt(8)
	s_barrier
	s_waitcnt vmcnt(6)
	s_cmpk_lt_u32 s9, 0x100
	s_sext_i32_i8 s5, s8
	v_bitop3_b32 v2, v0, s24, v1 bitop3:0xde
	v_bitop3_b32 v162, v0, s11, v1 bitop3:0xde
	s_cselect_b64 s[24:25], -1, 0
	v_readlane_b32 s8, v251, 0
	s_add_i32 s51, 0, 0x10000
	s_add_i32 s52, 0, 0x14000
	s_lshl_b32 s49, s10, 17
	s_add_i32 s50, s8, s2
	v_add_u32_e32 v163, s51, v162
	v_add_u32_e32 v164, s52, v162
	v_add_u32_e32 v165, 0, v2
	s_add_i32 s53, s0, 0xc000
	s_add_i32 s54, s0, 0xe000
	s_mov_b64 s[30:31], s[6:7]
	s_barrier
	v_readlane_b32 s9, v251, 1
	s_branch .LBB0_391

.LBB0_406:
	s_lshl_b32 s9, s15, 5
	s_mov_b64 s[20:21], 0x80
	s_and_b32 s41, s9, 0x60
	s_add_i32 m0, s35, 0x18000
	v_lshl_add_u64 v[6:7], v[6:7], 0, s[20:21]
	s_lshl_b32 s24, s14, 13
	s_lshl_b32 s15, s41, 7
	global_load_lds_dwordx4 v[6:7], off
	v_lshl_add_u64 v[4:5], v[4:5], 0, s[20:21]
	s_add_i32 m0, s35, 0x1a000
	s_add_i32 s43, s35, 0x8000
	s_add_i32 s44, s35, 0xa000
	global_load_lds_dwordx4 v[4:5], off
	v_lshl_add_u64 v[0:1], v[0:1], 0, s[20:21]
	s_mov_b32 m0, s43
	s_add_u32 s22, s18, 0x20080
	global_load_lds_dwordx4 v[0:1], off
	v_lshl_add_u64 v[0:1], v[2:3], 0, s[20:21]
	s_mov_b32 m0, s44
	s_addc_u32 s23, s19, 0
	global_load_lds_dwordx4 v[0:1], off
	s_add_i32 m0, s35, 0x1c000
	v_lshl_add_u64 v[0:1], s[22:23], 0, v[132:133]
	global_load_lds_dwordx4 v[0:1], off
	v_lshl_add_u64 v[0:1], s[22:23], 0, v[128:129]
	s_add_i32 m0, s35, 0x1e000
	v_and_b32_e32 v143, 15, v8
	global_load_lds_dwordx4 v[0:1], off
	s_cmpk_lt_u32 s13, 0x100
	v_bfe_u32 v142, v8, 4, 2
	v_lshlrev_b32_e32 v0, 6, v143
	v_lshlrev_b32_e32 v1, 2, v8
	s_cselect_b64 s[22:23], -1, 0
	s_lshl_b32 s45, s14, 17
	v_lshl_or_b32 v0, v142, 4, v0
	v_and_b32_e32 v1, 32, v1
	s_waitcnt vmcnt(8)
	s_barrier
	s_waitcnt vmcnt(6)
	s_add_u32 s46, s36, 0x12000000
	s_sext_i32_i8 s9, s12
	v_bitop3_b32 v2, v0, s24, v1 bitop3:0xde
	v_bitop3_b32 v144, v0, s15, v1 bitop3:0xde
	s_addc_u32 s47, s37, 0
	v_readlane_b32 s12, v251, 0
	s_add_i32 s49, 0, 0x10000
	s_add_i32 s50, 0, 0x14000
	s_add_i32 s48, s12, s2
	v_add_u32_e32 v145, s49, v144
	v_add_u32_e32 v146, s50, v144
	v_add_u32_e32 v147, 0, v2
	s_add_i32 s51, s35, 0xc000
	s_add_i32 s52, s35, 0xe000
	s_mov_b64 s[28:29], s[10:11]
	s_barrier
	v_readlane_b32 s13, v251, 1
	s_branch .LBB0_409

.LBB0_424:
	s_lshl_b32 s6, s6, 5
	s_and_b32 s14, s6, 0x60
	s_mov_b64 s[6:7], 0x80
	s_add_i32 m0, s41, 0x18000
	v_lshl_add_u64 v[6:7], v[6:7], 0, s[6:7]
	s_lshl_b32 s11, s10, 13
	s_lshl_b32 s15, s14, 7
	global_load_lds_dwordx4 v[6:7], off
	v_lshl_add_u64 v[4:5], v[4:5], 0, s[6:7]
	s_add_i32 m0, s41, 0x1a000
	s_add_i32 s47, s41, 0x8000
	s_add_i32 s48, s41, 0xa000
	global_load_lds_dwordx4 v[4:5], off
	v_lshl_add_u64 v[0:1], v[0:1], 0, s[6:7]
	s_mov_b32 m0, s47
	s_add_u32 s12, s22, 0x20080
	global_load_lds_dwordx4 v[0:1], off
	v_lshl_add_u64 v[0:1], v[2:3], 0, s[6:7]
	s_mov_b32 m0, s48
	s_addc_u32 s13, s23, 0
	global_load_lds_dwordx4 v[0:1], off
	s_add_i32 m0, s41, 0x1c000
	v_lshl_add_u64 v[0:1], s[12:13], 0, v[132:133]
	global_load_lds_dwordx4 v[0:1], off
	v_lshl_add_u64 v[0:1], s[12:13], 0, v[128:129]
	s_add_i32 m0, s41, 0x1e000
	v_and_b32_e32 v139, 15, v8
	global_load_lds_dwordx4 v[0:1], off
	s_cmpk_lt_u32 s9, 0x100
	s_sext_i32_i8 s19, s8
	v_bfe_u32 v138, v8, 4, 2
	v_lshlrev_b32_e32 v0, 6, v139
	v_lshlrev_b32_e32 v1, 2, v8
	s_cselect_b64 s[8:9], -1, 0
	s_lshl_b32 s10, s10, 17
	v_lshl_or_b32 v0, v138, 4, v0
	v_and_b32_e32 v1, 32, v1
	s_waitcnt vmcnt(8)
	s_barrier
	s_waitcnt vmcnt(6)
	s_add_u32 s49, s36, 0x14000000
	v_bitop3_b32 v2, v0, s11, v1 bitop3:0xde
	v_bitop3_b32 v140, v0, s15, v1 bitop3:0xde
	s_addc_u32 s50, s37, 0
	s_add_i32 s52, 0, 0x10000
	s_add_i32 s53, 0, 0x14000
	s_or_b32 s51, s14, s10
	v_add_u32_e32 v141, s52, v140
	v_add_u32_e32 v142, s53, v140
	v_add_u32_e32 v143, 0, v2
	s_mov_b64 s[14:15], s[20:21]
	s_mov_b64 s[16:17], s[22:23]
	s_barrier
	s_branch .LBB0_427

.LBB0_866:
	v_and_b32_e32 v143, 15, v0
	s_add_u32 s40, s12, 0x1a000000
	v_bfe_u32 v144, v0, 4, 2
	v_lshlrev_b32_e32 v16, 6, v143
	v_lshlrev_b32_e32 v0, 2, v0
	s_addc_u32 s41, s13, 0
	v_lshl_or_b32 v16, v144, 4, v16
	s_lshl_b32 s8, s14, 13
	v_and_b32_e32 v0, 32, v0
	v_bitop3_b32 v17, v16, s8, v0 bitop3:0xde
	s_lshl_b32 s8, s11, 5
	s_and_b32 s8, s8, 0x60
	s_add_i32 m0, s31, 0x18000
	v_lshl_add_u64 v[8:9], v[8:9], 0, s[64:65]
	s_lshl_b32 s9, s8, 7
	global_load_lds_dwordx4 v[8:9], off
	v_lshl_add_u64 v[6:7], v[6:7], 0, s[64:65]
	s_add_i32 m0, s31, 0x1a000
	s_add_i32 s46, s31, 0x8000
	s_add_i32 s47, s31, 0xa000
	global_load_lds_dwordx4 v[6:7], off
	v_lshl_add_u64 v[2:3], v[2:3], 0, s[64:65]
	s_mov_b32 m0, s46
	s_add_u32 s16, s24, 0x80080
	global_load_lds_dwordx4 v[2:3], off
	v_lshl_add_u64 v[2:3], v[4:5], 0, s[64:65]
	s_mov_b32 m0, s47
	s_addc_u32 s17, s25, 0
	global_load_lds_dwordx4 v[2:3], off
	s_add_i32 m0, s31, 0x1c000
	v_lshl_add_u64 v[2:3], s[16:17], 0, v[132:133]
	global_load_lds_dwordx4 v[2:3], off
	v_lshl_add_u64 v[2:3], s[16:17], 0, v[136:137]
	s_add_i32 m0, s31, 0x1e000
	v_bitop3_b32 v145, v16, s9, v0 bitop3:0xde
	global_load_lds_dwordx4 v[2:3], off
	v_lshlrev_b32_e32 v0, 15, v10
	v_and_b32_e32 v0, 0xffff0000, v0
	v_lshl_add_u32 v0, v11, 12, v0
	v_and_b32_e32 v2, 1, v10
	v_lshl_or_b32 v0, v2, 6, v0
	s_cmpk_lt_u32 s10, 0x100
	v_lshl_add_u32 v138, v12, 1, v0
	v_lshlrev_b32_e32 v0, 15, v13
	s_cselect_b64 s[10:11], -1, 0
	s_add_u32 s49, s12, 0x1c000000
	v_and_b32_e32 v0, 0xffff0000, v0
	s_waitcnt vmcnt(8)
	s_barrier
	s_waitcnt vmcnt(6)
	s_addc_u32 s50, s13, 0
	s_lshl_b32 s9, s14, 17
	v_lshl_add_u32 v0, v14, 12, v0
	v_and_b32_e32 v2, 1, v13
	s_add_u32 s51, s12, 0xc600000
	v_lshl_or_b32 v0, v2, 6, v0
	s_addc_u32 s56, s13, 0
	s_or_b32 s58, s8, s9
	v_mov_b32_e32 v139, v1
	v_lshl_add_u32 v140, v15, 1, v0
	v_mov_b32_e32 v141, v1
	s_mov_b32 s59, 0
	v_add_u32_e32 v146, 0, v17
	v_readlane_b32 s22, v251, 18
	s_mov_b64 s[20:21], s[24:25]
	s_mov_b64 s[16:17], s[38:39]
	s_barrier
	v_readlane_b32 s23, v251, 19
	s_waitcnt vmcnt(0)
	s_branch .LBB0_869

.LBB0_1011:
	v_readlane_b32 s0, v251, 45
	v_readlane_b32 s1, v251, 46
	s_xor_b64 s[8:9], s[96:97], -1
	s_lshl_b64 s[0:1], s[0:1], 2
	s_add_u32 s12, s3, s0
	s_addc_u32 s13, s5, s1
	s_add_u32 s46, s3, 0x14000000
	s_addc_u32 s47, s5, 0
	v_writelane_b32 v250, s50, 1
	s_and_b64 s[0:1], s[50:51], exec
	v_and_b32_e32 v147, 15, v14
	v_writelane_b32 v250, s51, 2
	v_bfe_u32 v146, v14, 4, 2
	v_readlane_b32 s0, v250, 5
	v_readlane_b32 s1, v250, 6
	s_cselect_b32 s96, s1, s47
	s_cselect_b32 s97, s0, s46
	s_add_u32 s0, s12, 0xde04000
	s_addc_u32 s1, s13, 0
	s_add_u32 s3, s3, 0xe000000
	s_addc_u32 s50, s5, 0
	s_lshl_b32 s4, s4, 5
	v_lshlrev_b32_e32 v16, 6, v147
	v_lshlrev_b32_e32 v14, 2, v14
	s_and_b32 s51, s4, 0x60
	v_lshl_or_b32 v16, v146, 4, v16
	s_lshl_b32 s5, s11, 13
	v_and_b32_e32 v14, 32, v14
	s_lshl_b32 s4, s51, 7
	s_add_i32 m0, s35, 0x18000
	v_lshl_add_u64 v[8:9], v[8:9], 0, s[64:65]
	v_bitop3_b32 v17, v16, s5, v14 bitop3:0xde
	v_bitop3_b32 v148, v16, s4, v14 bitop3:0xde
	global_load_lds_dwordx4 v[8:9], off
	v_lshl_add_u64 v[6:7], v[6:7], 0, s[64:65]
	s_add_i32 m0, s35, 0x1a000
	s_add_i32 s4, s35, 0x8000
	s_add_i32 s5, s35, 0xa000
	global_load_lds_dwordx4 v[6:7], off
	v_lshl_add_u64 v[2:3], v[2:3], 0, s[64:65]
	s_mov_b32 m0, s4
	s_add_u32 s12, s20, 0x80080
	global_load_lds_dwordx4 v[2:3], off
	v_lshl_add_u64 v[2:3], v[4:5], 0, s[64:65]
	s_mov_b32 m0, s5
	s_addc_u32 s13, s21, 0
	global_load_lds_dwordx4 v[2:3], off
	s_add_i32 m0, s35, 0x1c000
	v_lshl_add_u64 v[2:3], s[12:13], 0, v[134:135]
	global_load_lds_dwordx4 v[2:3], off
	v_lshl_add_u64 v[2:3], s[12:13], 0, v[130:131]
	s_add_i32 m0, s35, 0x1e000
	s_cmpk_lt_u32 s10, 0x100
	global_load_lds_dwordx4 v[2:3], off
	v_lshlrev_b32_e32 v2, 15, v13
	v_and_b32_e32 v2, 0xffff0000, v2
	v_lshl_add_u32 v2, v12, 12, v2
	v_and_b32_e32 v3, 1, v13
	v_lshl_or_b32 v2, v3, 6, v2
	v_lshl_add_u32 v138, v15, 1, v2
	v_lshlrev_b32_e32 v2, 15, v0
	v_and_b32_e32 v2, 0xffff0000, v2
	s_waitcnt vmcnt(8)
	s_barrier
	s_waitcnt vmcnt(6)
	v_lshl_add_u32 v2, v10, 12, v2
	v_and_b32_e32 v0, 1, v0
	s_cselect_b64 s[38:39], -1, 0
	s_lshl_b32 s60, s11, 17
	v_lshl_or_b32 v0, v0, 6, v2
	v_readlane_b32 s10, v251, 3
	v_mov_b32_e32 v139, v1
	v_lshl_add_u32 v140, v11, 1, v0
	v_mov_b32_e32 v141, v1
	s_mov_b32 s56, 0
	v_add_u32_e32 v149, 0, v17
	v_readlane_b32 s25, v251, 24
	s_mov_b32 s24, s10
	s_mov_b64 s[14:15], s[18:19]
	s_mov_b64 s[16:17], s[20:21]
	s_barrier
	v_readlane_b32 s11, v251, 4
	s_branch .LBB0_1014

.LBB0_1141:
	v_and_b32_e32 v142, 15, v15
	s_add_u32 s36, s11, 0x1a000000
	v_bfe_u32 v143, v15, 4, 2
	v_lshlrev_b32_e32 v16, 6, v142
	v_lshlrev_b32_e32 v15, 2, v15
	s_addc_u32 s37, s12, 0
	v_lshl_or_b32 v16, v143, 4, v16
	s_lshl_b32 s11, s10, 13
	v_and_b32_e32 v15, 32, v15
	s_lshl_b32 s9, s9, 5
	v_bitop3_b32 v17, v16, s11, v15 bitop3:0xde
	s_and_b32 s11, s9, 0x60
	s_add_i32 m0, s26, 0x18000
	v_lshl_add_u64 v[8:9], v[8:9], 0, s[64:65]
	s_lshl_b32 s9, s11, 7
	global_load_lds_dwordx4 v[8:9], off
	v_lshl_add_u64 v[6:7], v[6:7], 0, s[64:65]
	s_add_i32 m0, s26, 0x1a000
	s_add_i32 s38, s26, 0x8000
	s_add_i32 s39, s26, 0xa000
	global_load_lds_dwordx4 v[6:7], off
	v_lshl_add_u64 v[2:3], v[2:3], 0, s[64:65]
	s_mov_b32 m0, s38
	s_add_u32 s12, s20, 0x80080
	global_load_lds_dwordx4 v[2:3], off
	v_lshl_add_u64 v[2:3], v[4:5], 0, s[64:65]
	s_mov_b32 m0, s39
	s_addc_u32 s13, s21, 0
	global_load_lds_dwordx4 v[2:3], off
	s_add_i32 m0, s26, 0x1c000
	v_lshl_add_u64 v[2:3], s[12:13], 0, v[134:135]
	global_load_lds_dwordx4 v[2:3], off
	v_lshl_add_u64 v[2:3], s[12:13], 0, v[130:131]
	s_add_i32 m0, s26, 0x1e000
	s_cmpk_lt_u32 s8, 0x100
	global_load_lds_dwordx4 v[2:3], off
	v_lshlrev_b32_e32 v2, 15, v13
	v_and_b32_e32 v2, 0xffff0000, v2
	v_lshl_add_u32 v2, v12, 12, v2
	v_and_b32_e32 v3, 1, v13
	v_lshl_or_b32 v2, v3, 6, v2
	v_lshl_add_u32 v138, v14, 1, v2
	v_lshlrev_b32_e32 v2, 15, v0
	v_and_b32_e32 v2, 0xffff0000, v2
	v_bitop3_b32 v144, v16, s9, v15 bitop3:0xde
	s_waitcnt vmcnt(8)
	s_barrier
	s_waitcnt vmcnt(6)
	s_cselect_b64 s[8:9], -1, 0
	s_lshl_b32 s10, s10, 19
	v_lshl_add_u32 v2, v10, 12, v2
	v_and_b32_e32 v0, 1, v0
	s_or_b32 s40, s11, s10
	v_lshl_or_b32 v0, v0, 6, v2
	v_readlane_b32 s10, v251, 25
	v_mov_b32_e32 v139, v1
	v_lshl_add_u32 v140, v11, 1, v0
	v_mov_b32_e32 v141, v1
	s_mov_b32 s41, 0
	v_add_u32_e32 v145, 0, v17
	v_readlane_b32 s47, v251, 2
	s_mov_b32 s49, s10
	s_mov_b64 s[14:15], s[18:19]
	s_mov_b64 s[16:17], s[20:21]
	s_barrier
	v_readlane_b32 s11, v251, 26
	s_branch .LBB0_1144

.LBB0_1210:
	s_mul_i32 s13, s60, 0x30000
	s_add_u32 s13, s11, s13
	s_addc_u32 s14, s12, 0
	s_add_u32 s36, s11, 0xe000000
	s_addc_u32 s37, s12, 0
	s_add_u32 s40, s13, 0xde0a000
	s_addc_u32 s41, s14, 0
	s_add_u32 s46, s11, 0x14000000
	s_addc_u32 s47, s12, 0
	s_lshl_b32 s9, s9, 5
	s_and_b32 s49, s9, 0x60
	s_add_i32 m0, s26, 0x18000
	v_lshl_add_u64 v[8:9], v[8:9], 0, s[64:65]
	s_lshl_b32 s11, s10, 13
	s_lshl_b32 s9, s49, 7
	global_load_lds_dwordx4 v[8:9], off
	v_lshl_add_u64 v[6:7], v[6:7], 0, s[64:65]
	s_add_i32 m0, s26, 0x1a000
	s_add_i32 s50, s26, 0x8000
	s_add_i32 s51, s26, 0xa000
	global_load_lds_dwordx4 v[6:7], off
	v_lshl_add_u64 v[2:3], v[2:3], 0, s[64:65]
	s_mov_b32 m0, s50
	s_add_u32 s12, s20, 0x200080
	global_load_lds_dwordx4 v[2:3], off
	v_lshl_add_u64 v[2:3], v[4:5], 0, s[64:65]
	s_mov_b32 m0, s51
	s_addc_u32 s13, s21, 0
	global_load_lds_dwordx4 v[2:3], off
	s_add_i32 m0, s26, 0x1c000
	v_lshl_add_u64 v[2:3], s[12:13], 0, v[134:135]
	global_load_lds_dwordx4 v[2:3], off
	v_lshl_add_u64 v[2:3], s[12:13], 0, v[130:131]
	s_add_i32 m0, s26, 0x1e000
	v_and_b32_e32 v147, 15, v14
	global_load_lds_dwordx4 v[2:3], off
	v_lshlrev_b32_e32 v2, 17, v13
	v_and_b32_e32 v2, 0xfffc0000, v2
	v_lshl_add_u32 v2, v12, 14, v2
	v_and_b32_e32 v3, 1, v13
	v_lshl_or_b32 v2, v3, 6, v2
	v_lshl_add_u32 v138, v15, 1, v2
	v_lshlrev_b32_e32 v2, 17, v0
	v_bfe_u32 v146, v14, 4, 2
	v_lshlrev_b32_e32 v16, 6, v147
	v_lshlrev_b32_e32 v14, 2, v14
	v_and_b32_e32 v2, 0xfffc0000, v2
	v_lshl_or_b32 v16, v146, 4, v16
	v_and_b32_e32 v14, 32, v14
	s_waitcnt vmcnt(8)
	s_barrier
	s_waitcnt vmcnt(6)
	s_cmpk_lt_u32 s8, 0x100
	v_lshl_add_u32 v2, v10, 14, v2
	v_and_b32_e32 v0, 1, v0
	v_bitop3_b32 v17, v16, s11, v14 bitop3:0xde
	v_bitop3_b32 v148, v16, s9, v14 bitop3:0xde
	s_cselect_b64 s[8:9], -1, 0
	s_lshl_b32 s56, s10, 17
	v_lshl_or_b32 v0, v0, 6, v2
	v_readlane_b32 s10, v251, 3
	v_mov_b32_e32 v139, v1
	v_lshl_add_u32 v140, v11, 1, v0
	v_mov_b32_e32 v141, v1
	s_mov_b32 s58, 0
	v_add_u32_e32 v149, 0, v17
	v_readlane_b32 s39, v251, 24
	s_mov_b32 s38, s10
	s_mov_b64 s[14:15], s[18:19]
	s_mov_b64 s[16:17], s[20:21]
	s_barrier
	v_readlane_b32 s11, v251, 4
	s_branch .LBB0_1213
